# K-loop per-segment setprio flips deleted and one static s_setprio 1 for waves 4-7 across each GEMM phase (plus the attention-phase raise); loop alignment unchanged
# baseline (speedup 1.0000x reference)
; __global__ void __launch_bounds__(NTHREADS, 2) fwd_kernel(Args a) {
;     ...
;             for (int u0 = bid; u0 < 512; u0 += G, ++ucount) {
.LBB0_167:
	s_setprio 0
	s_nop 0
	s_nop 0
	s_nop 0
	s_nop 0
	s_nop 0
	s_nop 0
	s_nop 0
	s_nop 0
	s_nop 0
	s_nop 0
	s_nop 0
	s_nop 0
	s_nop 0
	s_mov_b64 s[10:11], 0

; #define PG8_STAGE(bufoff, gbase, voff) do { _Pragma("unroll") for (int _i = 0; _i < 2; ++_i) \
;         __builtin_amdgcn_global_load_lds((const unsigned*)((const char*)(gbase) + (voff)[_i]), (LAS unsigned*)(lds + (bufoff) + ldsw + _i * 8192), 16, 0, 0); } while (0)
; #define PG8_BAR __builtin_amdgcn_s_barrier()
; __device__ __forceinline__ void gemm_phase(LAS unsigned char* lds, const Gemm g, const StaticOrder& S_, const Epi& E, const int tid) {
;     ...
;     PG8_STAGE(PG8_SB(0, 0), cB, voffB); PG8_STAGE(PG8_SB(0, 1), cB + hstep, voffB); PG8_STAGE(PG8_SA(0, 0), cA, voffA); PG8_STAGE(PG8_SA(0, 1), cA + hstep, voffA);
;     PG8_RSTAB(cur, 0);
;     if (wr == 1) PG8_BAR;
.LBB0_210:
	v_writelane_b32 v236, s18, 33
	s_nop 1
	v_writelane_b32 v236, s19, 34
	s_or_b64 exec, exec, s[0:1]
	s_ashr_i32 s0, s23, 8
	v_mov_b32_e32 v189, v1
	v_mov_b32_e32 v193, v1
	v_mov_b32_e32 v187, v1
	v_mov_b32_e32 v191, v1
	s_cmp_eq_u32 s0, 1
	v_lshl_add_u64 v[6:7], s[20:21], 0, v[188:189]
	v_lshl_add_u64 v[8:9], s[20:21], 0, v[192:193]
	v_lshl_add_u64 v[4:5], s[10:11], 0, v[188:189]
	v_lshl_add_u64 v[2:3], s[10:11], 0, v[192:193]
	v_lshl_add_u64 v[10:11], s[38:39], 0, v[186:187]
	s_cselect_b64 s[30:31], -1, 0
	s_cmp_lg_u32 s0, 1
	v_lshl_add_u64 v[12:13], s[38:39], 0, v[190:191]
	s_cbranch_scc1 .LBB0_212
	s_barrier
	s_setprio 1
	s_nop 0

; #define PG8_WAIT_V(n) asm volatile("s_waitcnt vmcnt(" #n ")" ::: "memory")
; #define PG8_BAR __builtin_amdgcn_s_barrier()
; __device__ __forceinline__ void gemm_phase(LAS unsigned char* lds, const Gemm g, const StaticOrder& S_, const Epi& E, const int tid) {
;     ...
;     PG8_WAIT_V(0);
;     PG8_BAR;
.LBB0_270:
	s_setprio 0
	s_nop 0
	s_waitcnt vmcnt(0)
	v_readlane_b32 s38, v236, 7
	v_readlane_b32 s44, v236, 9
	v_readlane_b32 s30, v236, 14
	v_readlane_b32 s28, v236, 20
	v_readlane_b32 s18, v236, 33
	v_readlane_b32 s36, v236, 31
	v_readlane_b32 s53, v236, 22
	v_readlane_b32 s39, v236, 8
	v_readlane_b32 s45, v236, 10
	v_readlane_b32 s56, v236, 23
	v_readlane_b32 s40, v236, 11
	v_readlane_b32 s47, v236, 12
	v_readlane_b32 s48, v236, 13
	v_readlane_b32 s31, v236, 15
	v_readlane_b32 s29, v236, 21
	v_readlane_b32 s50, v236, 35
	v_readlane_b32 s19, v236, 34
	v_readlane_b32 s37, v236, 32
	s_barrier
